# mix-in phase: K and V column tiles swapped in the tile order so the V tiles (2-byte transposed stores) run on the workgroups that have two tiles instead of three
# baseline (speedup 1.0000x reference)
;     __device__ __forceinline__ bool next(int i, Unit& u) const {
;         const int L = lo + i * G + c; if (L >= hi) return false;
;         int pm, pn;
;         if (L < 640) pg8::static_map(L, 64, 10, pm, pn); else { const int e = L - 640; pm = 64 + (e >> 2); pn = 6 + (e & 3); }
;         u.pm = pm; u.pn = pn; u.z = 0; u.A = A + (size_t)pm * (256 * D * 2); u.B = B + (size_t)pn * (256 * D * 2); return true;
.LBB0_432:
	s_add_i32 s40, s40, 1
	s_mul_i32 s5, s40, s82
	s_add_i32 s5, s5, s84
	s_cmpk_lt_i32 s5, 0x280
	s_cselect_b64 s[28:29], -1, 0
	s_cmpk_gt_i32 s5, 0x27f
	s_cbranch_scc1 .LBB0_434
	s_ashr_i32 s10, s5, 31
	s_lshr_b32 s10, s10, 29
	s_add_i32 s10, s5, s10
	s_ashr_i32 s11, s10, 3
	s_and_b32 s10, s10, -8
	s_sub_i32 s5, s5, s10
	s_cmp_lt_i32 s5, 0
	s_cselect_b32 s10, s35, 0x50
	s_mul_i32 s5, s10, s5
	s_add_i32 s5, s5, s11
	s_mul_hi_i32 s10, s5, 0x66666667
	s_lshr_b32 s11, s10, 31
	s_ashr_i32 s10, s10, 5
	s_add_i32 s10, s10, s11
	s_lshl_b32 s11, s10, 3
	s_mulk_i32 s10, 0x50
	s_sub_i32 s5, s5, s10
	s_bfe_i32 s10, s5, 0x80000
	s_bfe_u32 s10, s10, 0x3000c
	s_add_i32 s22, s5, s10
	s_bfe_i32 s10, s22, 0x80000
	s_and_b32 s22, s22, 0xf8
	s_sub_i32 s5, s5, s22
	s_sext_i32_i8 s5, s5
	s_sext_i32_i16 s23, s10
	s_add_i32 s22, s11, s5
	s_lshr_b32 s10, s23, 3
	s_ashr_i32 s54, s23, 3
	s_cmp_gt_u32 s10, 7
	s_cselect_b32 s98, -2, 2
	s_cmp_gt_u32 s10, 5
	s_cselect_b32 s98, s98, 0
	s_add_i32 s10, s10, s98
	s_add_i32 s54, s54, s98
	s_ashr_i32 s23, s22, 31
	s_lshl_b64 s[24:25], s[22:23], 19
	s_add_u32 s24, s72, s24
	s_addc_u32 s25, s73, s25
	s_bfe_i64 s[10:11], s[10:11], 0x100000
	s_lshl_b64 s[10:11], s[10:11], 19
	s_add_u32 s26, s33, s10
	s_addc_u32 s27, s50, s11
